# placement sweep: both attention loop heads at 48 mod 64
# speedup vs baseline: 1.0009x; 1.0009x over previous
.LBB0_539:
	v_add_f32_e32 v16, 0, v32
	v_add_f32_e32 v16, v33, v16
	v_add_f32_e32 v17, 0, v40
	v_add_f32_e32 v16, v34, v16
	v_add_f32_e32 v17, v41, v17
	v_add_f32_e32 v16, v35, v16
	v_add_f32_e32 v17, v42, v17
	v_add_f32_e32 v16, v36, v16
	v_add_f32_e32 v17, v43, v17
	v_add_f32_e32 v16, v37, v16
	v_add_f32_e32 v17, v44, v17
	v_add_f32_e32 v16, v38, v16
	v_add_f32_e32 v17, v45, v17
	v_add_f32_e32 v16, v39, v16
	v_add_f32_e32 v17, v46, v17
	v_add_f32_e32 v16, 0, v16
	v_add_f32_e32 v17, v47, v17
	v_add_f32_e32 v18, 0, v48
	v_add_f32_e32 v16, v17, v16
	v_add_f32_e32 v17, 0, v56
	v_add_f32_e32 v18, v49, v18
	v_add_f32_e32 v17, v57, v17
	v_add_f32_e32 v18, v50, v18
	v_add_f32_e32 v17, v58, v17
	v_add_f32_e32 v18, v51, v18
	v_add_f32_e32 v17, v59, v17
	v_add_f32_e32 v18, v52, v18
	v_add_f32_e32 v17, v60, v17
	v_add_f32_e32 v18, v53, v18
	v_add_f32_e32 v17, v61, v17
	v_add_f32_e32 v18, v54, v18
	s_waitcnt vmcnt(0)
	ds_write_b64 v216, v[64:65] offset:18432
	s_waitcnt lgkmcnt(0)
	ds_write_b64 v216, v[68:69] offset:27648
	ds_write2st64_b64 v217, v[66:67], v[70:71] offset0:36 offset1:54
	ds_write_b128 v213, v[144:147]
	v_add_f32_e32 v17, v62, v17
	v_add_f32_e32 v18, v55, v18
	s_waitcnt lgkmcnt(0)
	s_barrier
	v_add_f32_e32 v17, v63, v17
	v_add_f32_e32 v16, v18, v16
	v_mov_b32_e32 v31, 0
	v_cvt_pk_bf16_f32 v160, v32, v33
	v_cvt_pk_bf16_f32 v161, v34, v35
	v_cvt_pk_bf16_f32 v162, v36, v37
	v_cvt_pk_bf16_f32 v163, v38, v39
	v_cvt_pk_bf16_f32 v148, v40, v41
	v_cvt_pk_bf16_f32 v149, v42, v43
	v_cvt_pk_bf16_f32 v150, v44, v45
	v_cvt_pk_bf16_f32 v151, v46, v47
	v_cvt_pk_bf16_f32 v152, v48, v49
	v_cvt_pk_bf16_f32 v153, v50, v51
	v_cvt_pk_bf16_f32 v154, v52, v53
	v_cvt_pk_bf16_f32 v155, v54, v55
	v_add_f32_e32 v193, v17, v16
	v_cvt_pk_bf16_f32 v156, v56, v57
	v_cvt_pk_bf16_f32 v157, v58, v59
	v_cvt_pk_bf16_f32 v158, v60, v61
	v_cvt_pk_bf16_f32 v159, v62, v63
	s_andn2_b64 vcc, exec, s[80:81]
	s_cbranch_vccnz .LBB0_546
	v_mov_b32_e32 v32, 0
	s_mov_b32 s77, 0
	s_movk_i32 s15, 0x80
	s_mov_b64 s[6:7], 0x80
	v_mov_b32_e32 v33, v32
	v_mov_b32_e32 v34, v32
	v_mov_b32_e32 v35, v32
	v_mov_b32_e32 v36, v32
	v_mov_b32_e32 v37, v32
	v_mov_b32_e32 v38, v32
	v_mov_b32_e32 v39, v32
	v_mov_b32_e32 v40, v32
	v_mov_b32_e32 v41, v32
	v_mov_b32_e32 v42, v32
	v_mov_b32_e32 v43, v32
	v_mov_b32_e32 v44, v32
	v_mov_b32_e32 v45, v32
	v_mov_b32_e32 v46, v32
	v_mov_b32_e32 v47, v32
	v_mov_b32_e32 v64, v32
	v_mov_b32_e32 v65, v32
	v_mov_b32_e32 v66, v32
	v_mov_b32_e32 v67, v32
	v_mov_b32_e32 v68, v32
	v_mov_b32_e32 v69, v32
	v_mov_b32_e32 v70, v32
	v_mov_b32_e32 v71, v32
	v_mov_b32_e32 v72, v32
	v_mov_b32_e32 v73, v32
	v_mov_b32_e32 v74, v32
	v_mov_b32_e32 v75, v32
	v_mov_b32_e32 v76, v32
	v_mov_b32_e32 v77, v32
	v_mov_b32_e32 v78, v32
	v_mov_b32_e32 v79, v32
	v_mov_b32_e32 v48, v32
	v_mov_b32_e32 v49, v32
	v_mov_b32_e32 v50, v32
	v_mov_b32_e32 v51, v32
	v_mov_b32_e32 v52, v32
	v_mov_b32_e32 v53, v32
	v_mov_b32_e32 v54, v32
	v_mov_b32_e32 v55, v32
	v_mov_b32_e32 v56, v32
	v_mov_b32_e32 v57, v32
	v_mov_b32_e32 v58, v32
	v_mov_b32_e32 v59, v32
	v_mov_b32_e32 v60, v32
	v_mov_b32_e32 v61, v32
	v_mov_b32_e32 v62, v32
	v_mov_b32_e32 v63, v32
	v_mov_b32_e32 v16, v32
	v_mov_b32_e32 v17, v32
	v_mov_b32_e32 v18, v32
	v_mov_b32_e32 v19, v32
	v_mov_b32_e32 v20, v32
	v_mov_b32_e32 v21, v32
	v_mov_b32_e32 v22, v32
	v_mov_b32_e32 v23, v32
	v_mov_b32_e32 v24, v32
	v_mov_b32_e32 v25, v32
	v_mov_b32_e32 v26, v32
	v_mov_b32_e32 v27, v32
	v_mov_b32_e32 v28, v32
	v_mov_b32_e32 v29, v32
	v_mov_b32_e32 v30, v32
	v_mov_b32_e32 v31, v32
	v_mov_b32_e32 v142, 0
	s_branch .LBB0_542
	.p2align 6
	s_nop 0
	s_nop 0
	s_nop 0
	s_nop 0
	s_nop 0
	s_nop 0
	s_nop 0
	s_nop 0
	s_nop 0
	s_nop 0
	s_nop 0
	s_nop 0
